# gate-tile stores nt sc1; + no entry grid.sync
# speedup vs baseline: 1.0191x; 1.0191x over previous
; __device__ __forceinline__ float sigm(float v) { return __builtin_amdgcn_rcpf(1.0f + __builtin_amdgcn_exp2f(-LOG2E * v)); }
; __device__ __forceinline__ unsigned cvt_pk_bf16(float lo, float hi) { f32x2_t v = {lo, hi}; bf16x2_t b = __builtin_convertvector(v, bf16x2_t); return __builtin_bit_cast(unsigned, b); }
; template <int MODE> __device__ __forceinline__ float actf(float v) {
;     if (MODE == 1) return v * sigm(v);
;     if (MODE == 2) return fminf(1.0f + __builtin_amdgcn_exp2f(-LOG2E * v), 1e30f);
;     template <int MODE> __device__ __forceinline__ void run(const f32x4 (&acc)[2][2][4][2], const Unit& u, int wr, int wc, int fr, int fq) const {
;     ...
;         char* base = (MODE == 2) ? (char*)(O + (size_t)6 * ((size_t)MTOK * 512)) + ((size_t)(((pn - 12) * 128 + u.pm) * 8 + wid__)) * 16384
;                                  : (char*)(O + (size_t)t * ((size_t)MTOK * 512) + (size_t)u.pm * BM * 512 + (colt & 511));
;         unsigned off0 = (MODE == 2) ? (unsigned)((t__ & 63) * 16) : (unsigned)((wr * 64 + fr) * 512 + wc * 32 + 8 * fq) * 2u; asm volatile("" : "+v"(off0));
; #pragma unroll
;         for (int bj = 0; bj < 2; ++bj) {
; #pragma unroll
;             for (int ai = 0; ai < 2; ++ai)
; #pragma unroll
;                 for (int m = 0; m < 4; ++m) { const unsigned off = off0 + ((MODE == 2) ? (unsigned)(((ai * 4 + m) * 2 + bj) * 1024) : (unsigned)((ai * HALF + m * 16) * 512 + bj * HALF) * 2u);
;                     const f32x4 v0 = acc[ai][bj][m][0], v1 = acc[ai][bj][m][1];
;                     u32x4 w; w.x = cvt_pk_bf16(actf<MODE>(v0[0]), actf<MODE>(v0[1])); w.y = cvt_pk_bf16(actf<MODE>(v0[2]), actf<MODE>(v0[3]));
;                     w.z = cvt_pk_bf16(actf<MODE>(v1[0]), actf<MODE>(v1[1])); w.w = cvt_pk_bf16(actf<MODE>(v1[2]), actf<MODE>(v1[3]));
;                     *(u32x4*)(base + off) = w; }
.LBB0_403:
	v_mul_f32_e32 v12, 0xbfb8aa3b, v12
	v_mul_f32_e32 v13, 0xbfb8aa3b, v13
	v_exp_f32_e32 v12, v12
	v_exp_f32_e32 v13, v13
	v_mul_f32_e32 v14, 0xbfb8aa3b, v14
	v_mul_f32_e32 v15, 0xbfb8aa3b, v15
	v_mul_f32_e32 v8, 0xbfb8aa3b, v8
	v_mul_f32_e32 v9, 0xbfb8aa3b, v9
	v_exp_f32_e32 v14, v14
	v_exp_f32_e32 v15, v15
	v_exp_f32_e32 v8, v8
	v_exp_f32_e32 v9, v9
	v_mul_f32_e32 v10, 0xbfb8aa3b, v10
	v_mul_f32_e32 v11, 0xbfb8aa3b, v11
	v_add_f32_e32 v12, 1.0, v12
	v_add_f32_e32 v13, 1.0, v13
	v_exp_f32_e32 v10, v10
	v_exp_f32_e32 v11, v11
	v_mul_f32_e32 v76, 0xbfb8aa3b, v76
	v_mul_f32_e32 v77, 0xbfb8aa3b, v77
	v_min_f32_e32 v12, 0x7149f2ca, v12
	v_min_f32_e32 v13, 0x7149f2ca, v13
	v_exp_f32_e32 v76, v76
	v_exp_f32_e32 v77, v77
	v_cvt_pk_bf16_f32 v12, v12, v13
	v_add_f32_e32 v13, 1.0, v14
	v_add_f32_e32 v14, 1.0, v15
	v_add_f32_e32 v8, 1.0, v8
	v_add_f32_e32 v9, 1.0, v9
	v_mul_f32_e32 v78, 0xbfb8aa3b, v78
	v_mul_f32_e32 v79, 0xbfb8aa3b, v79
	v_mul_f32_e32 v72, 0xbfb8aa3b, v72
	v_mul_f32_e32 v73, 0xbfb8aa3b, v73
	v_min_f32_e32 v13, 0x7149f2ca, v13
	v_min_f32_e32 v14, 0x7149f2ca, v14
	v_min_f32_e32 v8, 0x7149f2ca, v8
	v_min_f32_e32 v9, 0x7149f2ca, v9
	v_mov_b32_e32 v142, v212
	s_lshl_b32 s60, s72, 7
	v_exp_f32_e32 v78, v78
	v_exp_f32_e32 v79, v79
	v_exp_f32_e32 v72, v72
	v_exp_f32_e32 v73, v73
	v_cvt_pk_bf16_f32 v13, v13, v14
	v_cvt_pk_bf16_f32 v14, v8, v9
	v_add_f32_e32 v8, 1.0, v10
	v_add_f32_e32 v9, 1.0, v11
	s_add_i32 s60, s60, s54
	v_readfirstlane_b32 s55, v142
	v_mul_f32_e32 v74, 0xbfb8aa3b, v74
	v_mul_f32_e32 v75, 0xbfb8aa3b, v75
	v_min_f32_e32 v8, 0x7149f2ca, v8
	v_min_f32_e32 v9, 0x7149f2ca, v9
	s_ashr_i32 s55, s55, 6
	s_lshl_b32 s54, s60, 3
	v_add_f32_e32 v76, 1.0, v76
	v_add_f32_e32 v77, 1.0, v77
	v_exp_f32_e32 v74, v74
	v_exp_f32_e32 v75, v75
	v_cvt_pk_bf16_f32 v15, v8, v9
	v_mul_f32_e32 v8, 0xbfb8aa3b, v68
	v_mul_f32_e32 v9, 0xbfb8aa3b, v69
	s_add_i32 s54, s54, s55
	v_min_f32_e32 v76, 0x7149f2ca, v76
	v_min_f32_e32 v77, 0x7149f2ca, v77
	v_exp_f32_e32 v8, v8
	v_exp_f32_e32 v9, v9
	s_addk_i32 s54, 0xd000
	v_cvt_pk_bf16_f32 v76, v76, v77
	v_add_f32_e32 v77, 1.0, v78
	v_add_f32_e32 v78, 1.0, v79
	v_add_f32_e32 v72, 1.0, v72
	v_add_f32_e32 v73, 1.0, v73
	v_mul_f32_e32 v10, 0xbfb8aa3b, v70
	v_mul_f32_e32 v11, 0xbfb8aa3b, v71
	s_ashr_i32 s55, s54, 31
	v_min_f32_e32 v77, 0x7149f2ca, v77
	v_min_f32_e32 v78, 0x7149f2ca, v78
	v_min_f32_e32 v72, 0x7149f2ca, v72
	v_min_f32_e32 v73, 0x7149f2ca, v73
	v_exp_f32_e32 v10, v10
	v_exp_f32_e32 v11, v11
	s_lshl_b64 s[54:55], s[54:55], 14
	v_lshlrev_b32_e32 v142, 4, v142
	v_cvt_pk_bf16_f32 v77, v77, v78
	v_cvt_pk_bf16_f32 v78, v72, v73
	v_add_f32_e32 v72, 1.0, v74
	v_add_f32_e32 v73, 1.0, v75
	s_add_u32 s54, s33, s54
	v_and_b32_e32 v142, 0x3f0, v142
	v_min_f32_e32 v72, 0x7149f2ca, v72
	v_min_f32_e32 v73, 0x7149f2ca, v73
	v_add_f32_e32 v8, 1.0, v8
	v_add_f32_e32 v9, 1.0, v9
	s_addc_u32 s55, s37, s55
	v_cvt_pk_bf16_f32 v79, v72, v73
	v_add_u32_e32 v72, 0x3800, v142
	v_min_f32_e32 v8, 0x7149f2ca, v8
	v_min_f32_e32 v9, 0x7149f2ca, v9
	v_mul_f32_e32 v126, 0xbfb8aa3b, v126
	v_mul_f32_e32 v127, 0xbfb8aa3b, v127
	v_mul_f32_e32 v118, 0xbfb8aa3b, v118
	v_mul_f32_e32 v119, 0xbfb8aa3b, v119
	v_mul_f32_e32 v110, 0xbfb8aa3b, v110
	v_mul_f32_e32 v111, 0xbfb8aa3b, v111
	v_mul_f32_e32 v102, 0xbfb8aa3b, v102
	v_mul_f32_e32 v103, 0xbfb8aa3b, v103
	v_mul_f32_e32 v92, 0xbfb8aa3b, v92
	v_mul_f32_e32 v93, 0xbfb8aa3b, v93
	v_mul_f32_e32 v84, 0xbfb8aa3b, v84
	v_mul_f32_e32 v85, 0xbfb8aa3b, v85
	global_store_dwordx4 v72, v[12:15], s[54:55] nt sc1
	v_cvt_pk_bf16_f32 v8, v8, v9
	v_add_f32_e32 v9, 1.0, v10
	v_add_f32_e32 v10, 1.0, v11
	v_mul_f32_e32 v11, 0xbfb8aa3b, v64
	v_mul_f32_e32 v13, 0xbfb8aa3b, v65
	v_exp_f32_e32 v126, v126
	v_exp_f32_e32 v127, v127
	v_exp_f32_e32 v118, v118
	v_exp_f32_e32 v119, v119
	v_exp_f32_e32 v110, v110
	v_exp_f32_e32 v111, v111
	v_exp_f32_e32 v102, v102
	v_exp_f32_e32 v103, v103
	v_exp_f32_e32 v92, v92
	v_exp_f32_e32 v93, v93
	v_exp_f32_e32 v84, v84
	v_exp_f32_e32 v85, v85
	v_exp_f32_e32 v11, v11
	v_exp_f32_e32 v13, v13
	v_mul_f32_e32 v128, 0xbfb8aa3b, v128
	v_mul_f32_e32 v129, 0xbfb8aa3b, v129
	v_mul_f32_e32 v122, 0xbfb8aa3b, v122
	v_mul_f32_e32 v123, 0xbfb8aa3b, v123
	v_mul_f32_e32 v120, 0xbfb8aa3b, v120
	v_mul_f32_e32 v121, 0xbfb8aa3b, v121
	v_mul_f32_e32 v114, 0xbfb8aa3b, v114
	v_mul_f32_e32 v115, 0xbfb8aa3b, v115
	v_mul_f32_e32 v112, 0xbfb8aa3b, v112
	v_mul_f32_e32 v113, 0xbfb8aa3b, v113
	v_mul_f32_e32 v106, 0xbfb8aa3b, v106
	v_mul_f32_e32 v107, 0xbfb8aa3b, v107
	v_mul_f32_e32 v104, 0xbfb8aa3b, v104
	v_mul_f32_e32 v105, 0xbfb8aa3b, v105
	v_mul_f32_e32 v98, 0xbfb8aa3b, v98
	v_mul_f32_e32 v99, 0xbfb8aa3b, v99
	v_mul_f32_e32 v94, 0xbfb8aa3b, v94
	v_mul_f32_e32 v95, 0xbfb8aa3b, v95
	v_mul_f32_e32 v88, 0xbfb8aa3b, v88
	v_mul_f32_e32 v89, 0xbfb8aa3b, v89
	v_mul_f32_e32 v86, 0xbfb8aa3b, v86
	v_mul_f32_e32 v87, 0xbfb8aa3b, v87
	v_mul_f32_e32 v80, 0xbfb8aa3b, v80
	v_mul_f32_e32 v81, 0xbfb8aa3b, v81
	v_exp_f32_e32 v128, v128
	v_exp_f32_e32 v129, v129
	v_exp_f32_e32 v122, v122
	v_exp_f32_e32 v123, v123
	v_exp_f32_e32 v120, v120
	v_exp_f32_e32 v121, v121
	v_exp_f32_e32 v114, v114
	v_exp_f32_e32 v115, v115
	v_exp_f32_e32 v112, v112
	v_exp_f32_e32 v113, v113
	v_exp_f32_e32 v106, v106
	v_exp_f32_e32 v107, v107
	v_exp_f32_e32 v104, v104
	v_exp_f32_e32 v105, v105
	v_exp_f32_e32 v98, v98
	v_exp_f32_e32 v99, v99
	v_exp_f32_e32 v94, v94
	v_exp_f32_e32 v95, v95
	v_exp_f32_e32 v88, v88
	v_exp_f32_e32 v89, v89
	v_exp_f32_e32 v86, v86
	v_exp_f32_e32 v87, v87
	v_exp_f32_e32 v80, v80
	v_exp_f32_e32 v81, v81
	v_mul_f32_e32 v124, 0xbfb8aa3b, v124
	v_mul_f32_e32 v125, 0xbfb8aa3b, v125
	v_mul_f32_e32 v116, 0xbfb8aa3b, v116
; __device__ __forceinline__ unsigned cvt_pk_bf16(float lo, float hi) { f32x2_t v = {lo, hi}; bf16x2_t b = __builtin_convertvector(v, bf16x2_t); return __builtin_bit_cast(unsigned, b); }
;     template <int MODE> __device__ __forceinline__ void run(const f32x4 (&acc)[2][2][4][2], const Unit& u, int wr, int wc, int fr, int fq) const {
;     ...
;                 for (int m = 0; m < 4; ++m) { const unsigned off = off0 + ((MODE == 2) ? (unsigned)(((ai * 4 + m) * 2 + bj) * 1024) : (unsigned)((ai * HALF + m * 16) * 512 + bj * HALF) * 2u);
;                     const f32x4 v0 = acc[ai][bj][m][0], v1 = acc[ai][bj][m][1];
;                     u32x4 w; w.x = cvt_pk_bf16(actf<MODE>(v0[0]), actf<MODE>(v0[1])); w.y = cvt_pk_bf16(actf<MODE>(v0[2]), actf<MODE>(v0[3]));
;                     w.z = cvt_pk_bf16(actf<MODE>(v1[0]), actf<MODE>(v1[1])); w.w = cvt_pk_bf16(actf<MODE>(v1[2]), actf<MODE>(v1[3]));
;                     *(u32x4*)(base + off) = w; }
	v_mul_f32_e32 v117, 0xbfb8aa3b, v117
	v_mul_f32_e32 v108, 0xbfb8aa3b, v108
	v_mul_f32_e32 v109, 0xbfb8aa3b, v109
	v_mul_f32_e32 v100, 0xbfb8aa3b, v100
	v_mul_f32_e32 v101, 0xbfb8aa3b, v101
	v_mul_f32_e32 v90, 0xbfb8aa3b, v90
	v_mul_f32_e32 v91, 0xbfb8aa3b, v91
	v_mul_f32_e32 v82, 0xbfb8aa3b, v82
	v_mul_f32_e32 v83, 0xbfb8aa3b, v83
	v_min_f32_e32 v9, 0x7149f2ca, v9
	v_min_f32_e32 v10, 0x7149f2ca, v10
	v_add_f32_e32 v126, 1.0, v126
	v_add_f32_e32 v127, 1.0, v127
	v_exp_f32_e32 v124, v124
	v_exp_f32_e32 v125, v125
	v_add_f32_e32 v118, 1.0, v118
	v_add_f32_e32 v119, 1.0, v119
	v_exp_f32_e32 v116, v116
	v_exp_f32_e32 v117, v117
	v_add_f32_e32 v110, 1.0, v110
	v_add_f32_e32 v111, 1.0, v111
	v_exp_f32_e32 v108, v108
	v_exp_f32_e32 v109, v109
	v_add_f32_e32 v102, 1.0, v102
	v_add_f32_e32 v103, 1.0, v103
	v_exp_f32_e32 v100, v100
	v_exp_f32_e32 v101, v101
	v_add_f32_e32 v92, 1.0, v92
	v_add_f32_e32 v93, 1.0, v93
	v_exp_f32_e32 v90, v90
	v_exp_f32_e32 v91, v91
	v_add_f32_e32 v84, 1.0, v84
	v_add_f32_e32 v85, 1.0, v85
	v_exp_f32_e32 v82, v82
	v_exp_f32_e32 v83, v83
	v_cvt_pk_bf16_f32 v9, v9, v10
	v_add_f32_e32 v10, 1.0, v11
	v_add_f32_e32 v11, 1.0, v13
	v_mul_f32_e32 v13, 0xbfb8aa3b, v66
	v_mul_f32_e32 v14, 0xbfb8aa3b, v67
	v_min_f32_e32 v126, 0x7149f2ca, v126
	v_min_f32_e32 v127, 0x7149f2ca, v127
	v_min_f32_e32 v118, 0x7149f2ca, v118
	v_min_f32_e32 v119, 0x7149f2ca, v119
	v_min_f32_e32 v110, 0x7149f2ca, v110
	v_min_f32_e32 v111, 0x7149f2ca, v111
	v_min_f32_e32 v102, 0x7149f2ca, v102
	v_min_f32_e32 v103, 0x7149f2ca, v103
	v_min_f32_e32 v92, 0x7149f2ca, v92
	v_min_f32_e32 v93, 0x7149f2ca, v93
	v_min_f32_e32 v84, 0x7149f2ca, v84
	v_min_f32_e32 v85, 0x7149f2ca, v85
	v_exp_f32_e32 v13, v13
	v_exp_f32_e32 v14, v14
	v_cvt_pk_bf16_f32 v126, v126, v127
	v_add_f32_e32 v127, 1.0, v128
	v_add_f32_e32 v128, 1.0, v129
	v_add_f32_e32 v122, 1.0, v122
	v_add_f32_e32 v123, 1.0, v123
	v_cvt_pk_bf16_f32 v118, v118, v119
	v_add_f32_e32 v119, 1.0, v120
	v_add_f32_e32 v120, 1.0, v121
	v_add_f32_e32 v114, 1.0, v114
	v_add_f32_e32 v115, 1.0, v115
	v_cvt_pk_bf16_f32 v110, v110, v111
	v_add_f32_e32 v111, 1.0, v112
	v_add_f32_e32 v112, 1.0, v113
	v_add_f32_e32 v106, 1.0, v106
	v_add_f32_e32 v107, 1.0, v107
	v_cvt_pk_bf16_f32 v102, v102, v103
	v_add_f32_e32 v103, 1.0, v104
	v_add_f32_e32 v104, 1.0, v105
	v_add_f32_e32 v98, 1.0, v98
	v_add_f32_e32 v99, 1.0, v99
	v_cvt_pk_bf16_f32 v92, v92, v93
	v_add_f32_e32 v93, 1.0, v94
	v_add_f32_e32 v94, 1.0, v95
	v_add_f32_e32 v88, 1.0, v88
	v_add_f32_e32 v89, 1.0, v89
	v_cvt_pk_bf16_f32 v84, v84, v85
	v_add_f32_e32 v85, 1.0, v86
	v_add_f32_e32 v86, 1.0, v87
	v_add_f32_e32 v80, 1.0, v80
	v_add_f32_e32 v81, 1.0, v81
	v_min_f32_e32 v127, 0x7149f2ca, v127
	v_min_f32_e32 v128, 0x7149f2ca, v128
	v_min_f32_e32 v122, 0x7149f2ca, v122
	v_min_f32_e32 v123, 0x7149f2ca, v123
	v_min_f32_e32 v119, 0x7149f2ca, v119
	v_min_f32_e32 v120, 0x7149f2ca, v120
	v_min_f32_e32 v114, 0x7149f2ca, v114
	v_min_f32_e32 v115, 0x7149f2ca, v115
	v_min_f32_e32 v111, 0x7149f2ca, v111
	v_min_f32_e32 v112, 0x7149f2ca, v112
	v_min_f32_e32 v106, 0x7149f2ca, v106
	v_min_f32_e32 v107, 0x7149f2ca, v107
	v_min_f32_e32 v103, 0x7149f2ca, v103
	v_min_f32_e32 v104, 0x7149f2ca, v104
	v_min_f32_e32 v98, 0x7149f2ca, v98
	v_min_f32_e32 v99, 0x7149f2ca, v99
	v_min_f32_e32 v93, 0x7149f2ca, v93
	v_min_f32_e32 v94, 0x7149f2ca, v94
	v_min_f32_e32 v88, 0x7149f2ca, v88
	v_min_f32_e32 v89, 0x7149f2ca, v89
	v_min_f32_e32 v85, 0x7149f2ca, v85
	v_min_f32_e32 v86, 0x7149f2ca, v86
	v_min_f32_e32 v80, 0x7149f2ca, v80
	v_min_f32_e32 v81, 0x7149f2ca, v81
	v_cvt_pk_bf16_f32 v127, v127, v128
	v_cvt_pk_bf16_f32 v128, v122, v123
	v_add_f32_e32 v122, 1.0, v124
	v_add_f32_e32 v123, 1.0, v125
	v_cvt_pk_bf16_f32 v119, v119, v120
	v_cvt_pk_bf16_f32 v120, v114, v115
	v_add_f32_e32 v114, 1.0, v116
	v_add_f32_e32 v115, 1.0, v117
	v_cvt_pk_bf16_f32 v111, v111, v112
	v_cvt_pk_bf16_f32 v112, v106, v107
	v_add_f32_e32 v106, 1.0, v108
	v_add_f32_e32 v107, 1.0, v109
	v_cvt_pk_bf16_f32 v103, v103, v104
	v_cvt_pk_bf16_f32 v104, v98, v99
	v_add_f32_e32 v98, 1.0, v100
	v_add_f32_e32 v99, 1.0, v101
	v_cvt_pk_bf16_f32 v93, v93, v94
	v_cvt_pk_bf16_f32 v94, v88, v89
	v_add_f32_e32 v88, 1.0, v90
	v_add_f32_e32 v89, 1.0, v91
	v_cvt_pk_bf16_f32 v85, v85, v86
	v_cvt_pk_bf16_f32 v86, v80, v81
	v_add_f32_e32 v80, 1.0, v82
	v_add_f32_e32 v81, 1.0, v83
	v_min_f32_e32 v10, 0x7149f2ca, v10
	v_min_f32_e32 v11, 0x7149f2ca, v11
	v_min_f32_e32 v122, 0x7149f2ca, v122
	v_min_f32_e32 v123, 0x7149f2ca, v123
	v_min_f32_e32 v114, 0x7149f2ca, v114
	v_min_f32_e32 v115, 0x7149f2ca, v115
	v_min_f32_e32 v106, 0x7149f2ca, v106
	v_min_f32_e32 v107, 0x7149f2ca, v107
	v_min_f32_e32 v98, 0x7149f2ca, v98
	v_min_f32_e32 v99, 0x7149f2ca, v99
	v_min_f32_e32 v88, 0x7149f2ca, v88
	v_min_f32_e32 v89, 0x7149f2ca, v89
	v_min_f32_e32 v80, 0x7149f2ca, v80
	v_min_f32_e32 v81, 0x7149f2ca, v81
	v_cvt_pk_bf16_f32 v10, v10, v11
	v_add_f32_e32 v11, 1.0, v13
	v_add_f32_e32 v13, 1.0, v14
	v_cvt_pk_bf16_f32 v129, v122, v123
	v_add_u32_e32 v122, 0x800, v142
	v_cvt_pk_bf16_f32 v121, v114, v115
	v_add_u32_e32 v114, 0x1000, v142
	v_cvt_pk_bf16_f32 v113, v106, v107
	v_add_u32_e32 v106, 0x1800, v142
	v_cvt_pk_bf16_f32 v105, v98, v99
	v_add_u32_e32 v98, 0x2000, v142
	v_cvt_pk_bf16_f32 v95, v88, v89
	v_add_u32_e32 v88, 0x2800, v142
	v_cvt_pk_bf16_f32 v87, v80, v81
	v_add_u32_e32 v80, 0x3000, v142
	v_min_f32_e32 v11, 0x7149f2ca, v11
	v_min_f32_e32 v13, 0x7149f2ca, v13
	global_store_dwordx4 v142, v[126:129], s[54:55] nt sc1
	global_store_dwordx4 v122, v[118:121], s[54:55] nt sc1
	global_store_dwordx4 v114, v[110:113], s[54:55] nt sc1
	global_store_dwordx4 v106, v[102:105], s[54:55] nt sc1
; __device__ __forceinline__ unsigned cvt_pk_bf16(float lo, float hi) { f32x2_t v = {lo, hi}; bf16x2_t b = __builtin_convertvector(v, bf16x2_t); return __builtin_bit_cast(unsigned, b); }
;     template <int MODE> __device__ __forceinline__ void run(const f32x4 (&acc)[2][2][4][2], const Unit& u, int wr, int wc, int fr, int fq) const {
;     ...
;                 for (int m = 0; m < 4; ++m) { const unsigned off = off0 + ((MODE == 2) ? (unsigned)(((ai * 4 + m) * 2 + bj) * 1024) : (unsigned)((ai * HALF + m * 16) * 512 + bj * HALF) * 2u);
;                     const f32x4 v0 = acc[ai][bj][m][0], v1 = acc[ai][bj][m][1];
;                     u32x4 w; w.x = cvt_pk_bf16(actf<MODE>(v0[0]), actf<MODE>(v0[1])); w.y = cvt_pk_bf16(actf<MODE>(v0[2]), actf<MODE>(v0[3]));
;                     w.z = cvt_pk_bf16(actf<MODE>(v1[0]), actf<MODE>(v1[1])); w.w = cvt_pk_bf16(actf<MODE>(v1[2]), actf<MODE>(v1[3]));
;                     *(u32x4*)(base + off) = w; }
	global_store_dwordx4 v98, v[92:95], s[54:55] nt sc1
	global_store_dwordx4 v88, v[84:87], s[54:55] nt sc1
	global_store_dwordx4 v80, v[76:79], s[54:55] nt sc1
	v_add_u32_e32 v12, 0x400, v142
	v_cvt_pk_bf16_f32 v11, v11, v13
	global_store_dwordx4 v12, v[8:11], s[54:55] nt sc1
	v_mul_f32_e32 v13, 0xbfb8aa3b, v57
	v_exp_f32_e32 v13, v13
	v_mul_f32_e32 v8, 0xbfb8aa3b, v60
	v_mul_f32_e32 v9, 0xbfb8aa3b, v61
	v_exp_f32_e32 v8, v8
	v_exp_f32_e32 v9, v9
	v_mul_f32_e32 v10, 0xbfb8aa3b, v62
	v_mul_f32_e32 v11, 0xbfb8aa3b, v63
	v_exp_f32_e32 v10, v10
	v_exp_f32_e32 v11, v11
	v_add_f32_e32 v8, 1.0, v8
	v_add_f32_e32 v9, 1.0, v9
	v_min_f32_e32 v8, 0x7149f2ca, v8
	v_min_f32_e32 v9, 0x7149f2ca, v9
	v_cvt_pk_bf16_f32 v8, v8, v9
	v_add_f32_e32 v9, 1.0, v10
	v_add_f32_e32 v10, 1.0, v11
	v_mul_f32_e32 v11, 0xbfb8aa3b, v56
	v_exp_f32_e32 v11, v11
	v_min_f32_e32 v9, 0x7149f2ca, v9
	v_min_f32_e32 v10, 0x7149f2ca, v10
	v_cvt_pk_bf16_f32 v9, v9, v10
	v_add_f32_e32 v10, 1.0, v11
	v_add_f32_e32 v11, 1.0, v13
	v_mul_f32_e32 v13, 0xbfb8aa3b, v58
	v_mul_f32_e32 v14, 0xbfb8aa3b, v59
	v_exp_f32_e32 v13, v13
	v_exp_f32_e32 v14, v14
	v_min_f32_e32 v10, 0x7149f2ca, v10
	v_min_f32_e32 v11, 0x7149f2ca, v11
	v_cvt_pk_bf16_f32 v10, v10, v11
	v_add_f32_e32 v11, 1.0, v13
	v_add_f32_e32 v13, 1.0, v14
	v_min_f32_e32 v11, 0x7149f2ca, v11
	v_min_f32_e32 v13, 0x7149f2ca, v13
	v_add_u32_e32 v12, 0xc00, v142
	v_cvt_pk_bf16_f32 v11, v11, v13
	global_store_dwordx4 v12, v[8:11], s[54:55] nt sc1
	v_mul_f32_e32 v13, 0xbfb8aa3b, v49
	v_exp_f32_e32 v13, v13
	v_mul_f32_e32 v8, 0xbfb8aa3b, v52
	v_mul_f32_e32 v9, 0xbfb8aa3b, v53
	v_exp_f32_e32 v8, v8
	v_exp_f32_e32 v9, v9
	v_mul_f32_e32 v10, 0xbfb8aa3b, v54
	v_mul_f32_e32 v11, 0xbfb8aa3b, v55
	v_exp_f32_e32 v10, v10
	v_exp_f32_e32 v11, v11
	v_add_f32_e32 v8, 1.0, v8
	v_add_f32_e32 v9, 1.0, v9
	v_min_f32_e32 v8, 0x7149f2ca, v8
	v_min_f32_e32 v9, 0x7149f2ca, v9
	v_cvt_pk_bf16_f32 v8, v8, v9
	v_add_f32_e32 v9, 1.0, v10
	v_add_f32_e32 v10, 1.0, v11
	v_mul_f32_e32 v11, 0xbfb8aa3b, v48
	v_exp_f32_e32 v11, v11
	v_min_f32_e32 v9, 0x7149f2ca, v9
	v_min_f32_e32 v10, 0x7149f2ca, v10
	v_cvt_pk_bf16_f32 v9, v9, v10
	v_add_f32_e32 v10, 1.0, v11
	v_add_f32_e32 v11, 1.0, v13
	v_mul_f32_e32 v13, 0xbfb8aa3b, v50
	v_mul_f32_e32 v14, 0xbfb8aa3b, v51
	v_exp_f32_e32 v13, v13
	v_exp_f32_e32 v14, v14
	v_min_f32_e32 v10, 0x7149f2ca, v10
	v_min_f32_e32 v11, 0x7149f2ca, v11
	v_cvt_pk_bf16_f32 v10, v10, v11
	v_add_f32_e32 v11, 1.0, v13
	v_add_f32_e32 v13, 1.0, v14
	v_min_f32_e32 v11, 0x7149f2ca, v11
	v_min_f32_e32 v13, 0x7149f2ca, v13
	v_add_u32_e32 v12, 0x1400, v142
	v_cvt_pk_bf16_f32 v11, v11, v13
	global_store_dwordx4 v12, v[8:11], s[54:55] nt sc1
	v_mul_f32_e32 v13, 0xbfb8aa3b, v41
	v_exp_f32_e32 v13, v13
	v_mul_f32_e32 v8, 0xbfb8aa3b, v44
	v_mul_f32_e32 v9, 0xbfb8aa3b, v45
	v_exp_f32_e32 v8, v8
	v_exp_f32_e32 v9, v9
	v_mul_f32_e32 v10, 0xbfb8aa3b, v46
	v_mul_f32_e32 v11, 0xbfb8aa3b, v47
	v_exp_f32_e32 v10, v10
	v_exp_f32_e32 v11, v11
	v_add_f32_e32 v8, 1.0, v8
	v_add_f32_e32 v9, 1.0, v9
	v_min_f32_e32 v8, 0x7149f2ca, v8
	v_min_f32_e32 v9, 0x7149f2ca, v9
	v_cvt_pk_bf16_f32 v8, v8, v9
	v_add_f32_e32 v9, 1.0, v10
	v_add_f32_e32 v10, 1.0, v11
	v_mul_f32_e32 v11, 0xbfb8aa3b, v40
	v_exp_f32_e32 v11, v11
	v_min_f32_e32 v9, 0x7149f2ca, v9
	v_min_f32_e32 v10, 0x7149f2ca, v10
	v_cvt_pk_bf16_f32 v9, v9, v10
	v_add_f32_e32 v10, 1.0, v11
	v_add_f32_e32 v11, 1.0, v13
	v_mul_f32_e32 v13, 0xbfb8aa3b, v42
	v_mul_f32_e32 v14, 0xbfb8aa3b, v43
	v_exp_f32_e32 v13, v13
	v_exp_f32_e32 v14, v14
	v_min_f32_e32 v10, 0x7149f2ca, v10
	v_min_f32_e32 v11, 0x7149f2ca, v11
	v_cvt_pk_bf16_f32 v10, v10, v11
	v_add_f32_e32 v11, 1.0, v13
	v_add_f32_e32 v13, 1.0, v14
	v_min_f32_e32 v11, 0x7149f2ca, v11
	v_min_f32_e32 v13, 0x7149f2ca, v13
	v_add_u32_e32 v12, 0x1c00, v142
	v_cvt_pk_bf16_f32 v11, v11, v13
	global_store_dwordx4 v12, v[8:11], s[54:55] nt sc1
	v_mul_f32_e32 v13, 0xbfb8aa3b, v33
	v_exp_f32_e32 v13, v13
	v_mul_f32_e32 v8, 0xbfb8aa3b, v36
	v_mul_f32_e32 v9, 0xbfb8aa3b, v37
	v_exp_f32_e32 v8, v8
	v_exp_f32_e32 v9, v9
	v_mul_f32_e32 v10, 0xbfb8aa3b, v38
	v_mul_f32_e32 v11, 0xbfb8aa3b, v39
	v_exp_f32_e32 v10, v10
	v_exp_f32_e32 v11, v11
	v_add_f32_e32 v8, 1.0, v8
	v_add_f32_e32 v9, 1.0, v9
	v_min_f32_e32 v8, 0x7149f2ca, v8
	v_min_f32_e32 v9, 0x7149f2ca, v9
	v_cvt_pk_bf16_f32 v8, v8, v9
; __device__ __forceinline__ unsigned cvt_pk_bf16(float lo, float hi) { f32x2_t v = {lo, hi}; bf16x2_t b = __builtin_convertvector(v, bf16x2_t); return __builtin_bit_cast(unsigned, b); }
;     template <int MODE> __device__ __forceinline__ void run(const f32x4 (&acc)[2][2][4][2], const Unit& u, int wr, int wc, int fr, int fq) const {
;     ...
;                 for (int m = 0; m < 4; ++m) { const unsigned off = off0 + ((MODE == 2) ? (unsigned)(((ai * 4 + m) * 2 + bj) * 1024) : (unsigned)((ai * HALF + m * 16) * 512 + bj * HALF) * 2u);
;                     const f32x4 v0 = acc[ai][bj][m][0], v1 = acc[ai][bj][m][1];
;                     u32x4 w; w.x = cvt_pk_bf16(actf<MODE>(v0[0]), actf<MODE>(v0[1])); w.y = cvt_pk_bf16(actf<MODE>(v0[2]), actf<MODE>(v0[3]));
;                     w.z = cvt_pk_bf16(actf<MODE>(v1[0]), actf<MODE>(v1[1])); w.w = cvt_pk_bf16(actf<MODE>(v1[2]), actf<MODE>(v1[3]));
;                     *(u32x4*)(base + off) = w; }
	v_add_f32_e32 v9, 1.0, v10
	v_add_f32_e32 v10, 1.0, v11
	v_mul_f32_e32 v11, 0xbfb8aa3b, v32
	v_exp_f32_e32 v11, v11
	v_min_f32_e32 v9, 0x7149f2ca, v9
	v_min_f32_e32 v10, 0x7149f2ca, v10
	v_cvt_pk_bf16_f32 v9, v9, v10
	v_add_f32_e32 v10, 1.0, v11
	v_add_f32_e32 v11, 1.0, v13
	v_mul_f32_e32 v13, 0xbfb8aa3b, v34
	v_mul_f32_e32 v14, 0xbfb8aa3b, v35
	v_exp_f32_e32 v13, v13
	v_exp_f32_e32 v14, v14
	v_min_f32_e32 v10, 0x7149f2ca, v10
	v_min_f32_e32 v11, 0x7149f2ca, v11
	v_cvt_pk_bf16_f32 v10, v10, v11
	v_add_f32_e32 v11, 1.0, v13
	v_add_f32_e32 v13, 1.0, v14
	v_min_f32_e32 v11, 0x7149f2ca, v11
	v_min_f32_e32 v13, 0x7149f2ca, v13
	v_add_u32_e32 v12, 0x2400, v142
	v_cvt_pk_bf16_f32 v11, v11, v13
	global_store_dwordx4 v12, v[8:11], s[54:55] nt sc1
	v_mul_f32_e32 v13, 0xbfb8aa3b, v25
	v_exp_f32_e32 v13, v13
	v_mul_f32_e32 v8, 0xbfb8aa3b, v28
	v_mul_f32_e32 v9, 0xbfb8aa3b, v29
	v_exp_f32_e32 v8, v8
	v_exp_f32_e32 v9, v9
	v_mul_f32_e32 v10, 0xbfb8aa3b, v30
	v_mul_f32_e32 v11, 0xbfb8aa3b, v31
	v_exp_f32_e32 v10, v10
	v_exp_f32_e32 v11, v11
	v_add_f32_e32 v8, 1.0, v8
	v_add_f32_e32 v9, 1.0, v9
	v_min_f32_e32 v8, 0x7149f2ca, v8
	v_min_f32_e32 v9, 0x7149f2ca, v9
	v_cvt_pk_bf16_f32 v8, v8, v9
	v_add_f32_e32 v9, 1.0, v10
	v_add_f32_e32 v10, 1.0, v11
	v_mul_f32_e32 v11, 0xbfb8aa3b, v24
	v_exp_f32_e32 v11, v11
	v_min_f32_e32 v9, 0x7149f2ca, v9
	v_min_f32_e32 v10, 0x7149f2ca, v10
	v_cvt_pk_bf16_f32 v9, v9, v10
	v_add_f32_e32 v10, 1.0, v11
	v_add_f32_e32 v11, 1.0, v13
	v_mul_f32_e32 v13, 0xbfb8aa3b, v26
	v_mul_f32_e32 v14, 0xbfb8aa3b, v27
	v_exp_f32_e32 v13, v13
	v_exp_f32_e32 v14, v14
	v_min_f32_e32 v10, 0x7149f2ca, v10
	v_min_f32_e32 v11, 0x7149f2ca, v11
	v_cvt_pk_bf16_f32 v10, v10, v11
	v_add_f32_e32 v11, 1.0, v13
	v_add_f32_e32 v13, 1.0, v14
	v_min_f32_e32 v11, 0x7149f2ca, v11
	v_min_f32_e32 v13, 0x7149f2ca, v13
	v_add_u32_e32 v12, 0x2c00, v142
	v_cvt_pk_bf16_f32 v11, v11, v13
	global_store_dwordx4 v12, v[8:11], s[54:55] nt sc1
	v_mul_f32_e32 v13, 0xbfb8aa3b, v17
	v_exp_f32_e32 v13, v13
	v_mul_f32_e32 v8, 0xbfb8aa3b, v20
	v_mul_f32_e32 v9, 0xbfb8aa3b, v21
	v_exp_f32_e32 v8, v8
	v_exp_f32_e32 v9, v9
	v_mul_f32_e32 v10, 0xbfb8aa3b, v22
	v_mul_f32_e32 v11, 0xbfb8aa3b, v23
	v_exp_f32_e32 v10, v10
	v_exp_f32_e32 v11, v11
	v_add_f32_e32 v8, 1.0, v8
	v_add_f32_e32 v9, 1.0, v9
	v_min_f32_e32 v8, 0x7149f2ca, v8
	v_min_f32_e32 v9, 0x7149f2ca, v9
	v_cvt_pk_bf16_f32 v8, v8, v9
	v_add_f32_e32 v9, 1.0, v10
	v_add_f32_e32 v10, 1.0, v11
	v_mul_f32_e32 v11, 0xbfb8aa3b, v16
	v_exp_f32_e32 v11, v11
	v_mul_f32_e32 v4, 0xbfb8aa3b, v4
	v_mul_f32_e32 v5, 0xbfb8aa3b, v5
	v_exp_f32_e32 v4, v4
	v_exp_f32_e32 v5, v5
	v_min_f32_e32 v9, 0x7149f2ca, v9
	v_min_f32_e32 v10, 0x7149f2ca, v10
	v_mul_f32_e32 v6, 0xbfb8aa3b, v6
	v_mul_f32_e32 v7, 0xbfb8aa3b, v7
	v_mul_f32_e32 v0, 0xbfb8aa3b, v0
	v_mul_f32_e32 v1, 0xbfb8aa3b, v1
	v_cvt_pk_bf16_f32 v9, v9, v10
	v_add_f32_e32 v10, 1.0, v11
	v_add_f32_e32 v11, 1.0, v13
	v_mul_f32_e32 v13, 0xbfb8aa3b, v18
	v_mul_f32_e32 v14, 0xbfb8aa3b, v19
	v_exp_f32_e32 v6, v6
	v_exp_f32_e32 v7, v7
	v_exp_f32_e32 v0, v0
	v_exp_f32_e32 v1, v1
	v_exp_f32_e32 v13, v13
	v_exp_f32_e32 v14, v14
	v_mul_f32_e32 v2, 0xbfb8aa3b, v2
	v_mul_f32_e32 v3, 0xbfb8aa3b, v3
	v_add_f32_e32 v4, 1.0, v4
	v_add_f32_e32 v5, 1.0, v5
	v_exp_f32_e32 v2, v2
	v_exp_f32_e32 v3, v3
	v_min_f32_e32 v4, 0x7149f2ca, v4
	v_min_f32_e32 v5, 0x7149f2ca, v5
	v_min_f32_e32 v10, 0x7149f2ca, v10
	v_min_f32_e32 v11, 0x7149f2ca, v11
	v_cvt_pk_bf16_f32 v4, v4, v5
	v_add_f32_e32 v5, 1.0, v6
	v_add_f32_e32 v6, 1.0, v7
	v_add_f32_e32 v0, 1.0, v0
	v_add_f32_e32 v1, 1.0, v1
	v_cvt_pk_bf16_f32 v10, v10, v11
	v_add_f32_e32 v11, 1.0, v13
	v_add_f32_e32 v13, 1.0, v14
	v_min_f32_e32 v5, 0x7149f2ca, v5
	v_min_f32_e32 v6, 0x7149f2ca, v6
	v_min_f32_e32 v0, 0x7149f2ca, v0
	v_min_f32_e32 v1, 0x7149f2ca, v1
	v_min_f32_e32 v11, 0x7149f2ca, v11
	v_min_f32_e32 v13, 0x7149f2ca, v13
	v_cvt_pk_bf16_f32 v5, v5, v6
	v_cvt_pk_bf16_f32 v6, v0, v1
	v_add_f32_e32 v0, 1.0, v2
	v_add_f32_e32 v1, 1.0, v3
	v_add_u32_e32 v12, 0x3400, v142
	v_cvt_pk_bf16_f32 v11, v11, v13
	v_min_f32_e32 v0, 0x7149f2ca, v0
	v_min_f32_e32 v1, 0x7149f2ca, v1
	global_store_dwordx4 v12, v[8:11], s[54:55] nt sc1
	v_cvt_pk_bf16_f32 v7, v0, v1
	s_nop 0
	v_add_u32_e32 v8, 0x3c00, v142
	global_store_dwordx4 v8, v[4:7], s[54:55] nt sc1
